# A2 diff-attn unit epilogue: the 16 sub-LN gain loads issued together into dead VGPR quads with counted vmcnt(15) waits (was load/vmcnt(0)/store serialized 16x)
# speedup vs baseline: 1.0103x; 1.0092x over previous
; #define LAS __attribute__((address_space(3)))
; DI unsigned pk2(float a, float b) { f32x2 v = {a, b}; bf16x2_t r = __builtin_convertvector(v, bf16x2_t); return __builtin_bit_cast(unsigned, r); }
; DI float shx(float v, int o, int lane) { return __int_as_float(__builtin_amdgcn_ds_bpermute((lane ^ o) << 2, __float_as_int(v))); }
;     ...
;         __syncthreads();
;     }
;     ...
;     const float l = l_run + shx(l_run, 32, lane);
;     const float inv = 1.0f / l;
;     if (MODE == 0) {
; #pragma unroll
;         for (int db = 0; db < NDB; ++db)
; #pragma unroll
;             for (int g = 0; g < 4; ++g) { u32x2 o; o.x = pk2(ot[db][4 * g] * inv, ot[db][4 * g + 1] * inv); o.y = pk2(ot[db][4 * g + 2] * inv, ot[db][4 * g + 3] * inv);
;                 *(u32x2*)(obase + (rowbase + q0 + r) * ldo + wave * 64 + 32 * db + 8 * g + 4 * h) = o; }
;     } else {
;         LAS float* xch = (LAS float*)lds;
;         const int map = wave >> 2, sub = wave & 3;
;         if (map == 1) {
; #pragma unroll
;             for (int db = 0; db < NDB; ++db)
; #pragma unroll
;                 for (int i = 0; i < 16; ++i) xch[((sub * 4 + db) * 16 + i) * 64 + lane] = ot[db][i] * inv;
;         }
;         __syncthreads();
;         if (map == 0) {
;             float ss = 0.f;
; #pragma unroll
;             for (int db = 0; db < NDB; ++db)
; #pragma unroll
;                 for (int i = 0; i < 16; ++i) { const float o = ot[db][i] * inv - lam * xch[((sub * 4 + db) * 16 + i) * 64 + lane]; ot[db][i] = o; ss += o * o; }
.LBB0_513:
	s_andn2_b64 vcc, exec, s[8:9]
	s_waitcnt lgkmcnt(0)
	s_barrier
	s_cbranch_vccnz .LBB0_495
	ds_read2st64_b32 v[86:87], v163 offset1:1
	ds_read2st64_b32 v[96:97], v163 offset0:2 offset1:3
	s_waitcnt vmcnt(7)
	ds_read2st64_b32 v[100:101], v163 offset0:4 offset1:5
	ds_read2st64_b32 v[102:103], v163 offset0:6 offset1:7
	s_waitcnt vmcnt(3)
	ds_read2st64_b32 v[118:119], v163 offset0:8 offset1:9
	s_waitcnt vmcnt(2)
	ds_read2st64_b32 v[138:139], v163 offset0:10 offset1:11
	ds_read2st64_b32 v[76:77], v163 offset0:12 offset1:13
	s_waitcnt vmcnt(1)
	ds_read2st64_b32 v[140:141], v163 offset0:14 offset1:15
	ds_read2st64_b32 v[72:73], v163 offset0:16 offset1:17
	ds_read2st64_b32 v[88:89], v163 offset0:18 offset1:19
	ds_read2st64_b32 v[78:79], v163 offset0:20 offset1:21
	ds_read2st64_b32 v[136:137], v163 offset0:22 offset1:23
	s_waitcnt vmcnt(0)
	ds_read2st64_b32 v[130:131], v163 offset0:24 offset1:25
	ds_read2st64_b32 v[134:135], v163 offset0:26 offset1:27
	ds_read2st64_b32 v[124:125], v163 offset0:28 offset1:29
	ds_read2st64_b32 v[132:133], v163 offset0:30 offset1:31
	ds_read2st64_b32 v[120:121], v163 offset0:32 offset1:33
	ds_read2st64_b32 v[126:127], v163 offset0:34 offset1:35
	ds_read2st64_b32 v[112:113], v163 offset0:36 offset1:37
	ds_read2st64_b32 v[122:123], v163 offset0:38 offset1:39
	ds_read2st64_b32 v[104:105], v163 offset0:40 offset1:41
	ds_read2st64_b32 v[114:115], v163 offset0:42 offset1:43
	ds_read2st64_b32 v[94:95], v163 offset0:44 offset1:45
	ds_read2st64_b32 v[110:111], v163 offset0:46 offset1:47
	ds_read2st64_b32 v[90:91], v163 offset0:48 offset1:49
	ds_read2st64_b32 v[92:93], v163 offset0:50 offset1:51
	ds_read2st64_b32 v[80:81], v163 offset0:52 offset1:53
	ds_read2st64_b32 v[84:85], v163 offset0:54 offset1:55
	ds_read2st64_b32 v[74:75], v163 offset0:56 offset1:57
	ds_read2st64_b32 v[64:65], v163 offset0:58 offset1:59
	s_waitcnt lgkmcnt(14)
	v_pk_mul_f32 v[96:97], v[148:149], v[96:97]
	s_lshl_b32 s74, s20, 1
	v_pk_fma_f32 v[96:97], v[2:3], v[68:69], v[96:97] op_sel_hi:[1,0,1] neg_lo:[0,0,1] neg_hi:[0,0,1]
	v_pk_mul_f32 v[2:3], v[148:149], v[86:87]
	s_waitcnt lgkmcnt(0)
	v_pk_mul_f32 v[64:65], v[148:149], v[64:65]
	v_pk_fma_f32 v[106:107], v[0:1], v[68:69], v[2:3] op_sel_hi:[1,0,1] neg_lo:[0,0,1] neg_hi:[0,0,1]
	v_pk_fma_f32 v[64:65], v[26:27], v[68:69], v[64:65] op_sel_hi:[1,0,1] neg_lo:[0,0,1] neg_hi:[0,0,1]
	ds_read2st64_b32 v[26:27], v163 offset0:60 offset1:61
	v_pk_mul_f32 v[2:3], v[148:149], v[102:103]
	v_pk_mul_f32 v[144:145], v[106:107], v[106:107]
	v_pk_mul_f32 v[142:143], v[96:97], v[96:97]
	v_pk_mul_f32 v[70:71], v[64:65], v[64:65]
	s_waitcnt lgkmcnt(0)
	v_pk_mul_f32 v[26:27], v[148:149], v[26:27]
	s_nop 0
	v_pk_fma_f32 v[66:67], v[28:29], v[68:69], v[26:27] op_sel_hi:[1,0,1] neg_lo:[0,0,1] neg_hi:[0,0,1]
	ds_read2st64_b32 v[26:27], v163 offset0:62 offset1:63
	v_pk_mul_f32 v[82:83], v[66:67], v[66:67]
	s_waitcnt lgkmcnt(0)
	v_pk_mul_f32 v[26:27], v[148:149], v[26:27]
	s_nop 0
	v_pk_fma_f32 v[30:31], v[30:31], v[68:69], v[26:27] op_sel_hi:[1,0,1] neg_lo:[0,0,1] neg_hi:[0,0,1]
	v_lshl_add_u64 v[26:27], s[4:5], 0, v[188:189]
	v_lshl_add_u64 v[108:109], v[26:27], 0, s[74:75]
	v_lshl_add_u64 v[0:1], v[168:169], 1, v[108:109]
	v_pk_fma_f32 v[108:109], v[6:7], v[68:69], v[2:3] op_sel_hi:[1,0,1] neg_lo:[0,0,1] neg_hi:[0,0,1]
	v_pk_mul_f32 v[2:3], v[148:149], v[100:101]
	v_pk_mul_f32 v[146:147], v[108:109], v[108:109]
	v_pk_fma_f32 v[116:117], v[4:5], v[68:69], v[2:3] op_sel_hi:[1,0,1] neg_lo:[0,0,1] neg_hi:[0,0,1]
	v_pk_mul_f32 v[2:3], v[148:149], v[138:139]
	v_pk_mul_f32 v[188:189], v[116:117], v[116:117]
	v_pk_fma_f32 v[100:101], v[10:11], v[68:69], v[2:3] op_sel_hi:[1,0,1] neg_lo:[0,0,1] neg_hi:[0,0,1]
	v_pk_mul_f32 v[2:3], v[148:149], v[118:119]
	v_pk_mul_f32 v[138:139], v[100:101], v[100:101]
	v_pk_fma_f32 v[118:119], v[8:9], v[68:69], v[2:3] op_sel_hi:[1,0,1] neg_lo:[0,0,1] neg_hi:[0,0,1]
	v_pk_mul_f32 v[2:3], v[148:149], v[140:141]
	v_pk_mul_f32 v[190:191], v[118:119], v[118:119]
	v_pk_fma_f32 v[86:87], v[14:15], v[68:69], v[2:3] op_sel_hi:[1,0,1] neg_lo:[0,0,1] neg_hi:[0,0,1]
	v_pk_mul_f32 v[2:3], v[148:149], v[76:77]
	v_pk_mul_f32 v[140:141], v[86:87], v[86:87]
	v_pk_fma_f32 v[102:103], v[12:13], v[68:69], v[2:3] op_sel_hi:[1,0,1] neg_lo:[0,0,1] neg_hi:[0,0,1]
	v_pk_mul_f32 v[2:3], v[148:149], v[88:89]
	v_pk_mul_f32 v[192:193], v[102:103], v[102:103]
	v_pk_fma_f32 v[76:77], v[50:51], v[68:69], v[2:3] op_sel_hi:[1,0,1] neg_lo:[0,0,1] neg_hi:[0,0,1]
	v_pk_mul_f32 v[2:3], v[148:149], v[72:73]
	v_pk_mul_f32 v[194:195], v[76:77], v[76:77]
	v_pk_fma_f32 v[88:89], v[48:49], v[68:69], v[2:3] op_sel_hi:[1,0,1] neg_lo:[0,0,1] neg_hi:[0,0,1]
	v_pk_mul_f32 v[2:3], v[148:149], v[136:137]
	v_pk_mul_f32 v[196:197], v[88:89], v[88:89]
	v_pk_fma_f32 v[72:73], v[54:55], v[68:69], v[2:3] op_sel_hi:[1,0,1] neg_lo:[0,0,1] neg_hi:[0,0,1]
	v_pk_mul_f32 v[2:3], v[148:149], v[78:79]
	global_load_dwordx4 v[26:29], v[170:171], off
	v_pk_fma_f32 v[78:79], v[52:53], v[68:69], v[2:3] op_sel_hi:[1,0,1] neg_lo:[0,0,1] neg_hi:[0,0,1]
	v_pk_mul_f32 v[2:3], v[148:149], v[134:135]
	v_pk_mul_f32 v[200:201], v[78:79], v[78:79]
	v_pk_fma_f32 v[54:55], v[58:59], v[68:69], v[2:3] op_sel_hi:[1,0,1] neg_lo:[0,0,1] neg_hi:[0,0,1]
	v_pk_mul_f32 v[2:3], v[148:149], v[130:131]
	v_pk_mul_f32 v[136:137], v[72:73], v[72:73]
	v_pk_fma_f32 v[58:59], v[56:57], v[68:69], v[2:3] op_sel_hi:[1,0,1] neg_lo:[0,0,1] neg_hi:[0,0,1]
	v_pk_mul_f32 v[2:3], v[148:149], v[132:133]
	v_pk_mul_f32 v[130:131], v[58:59], v[58:59]
	v_pk_fma_f32 v[50:51], v[62:63], v[68:69], v[2:3] op_sel_hi:[1,0,1] neg_lo:[0,0,1] neg_hi:[0,0,1]
	v_pk_mul_f32 v[2:3], v[148:149], v[124:125]
; DI float shx(float v, int o, int lane) { return __int_as_float(__builtin_amdgcn_ds_bpermute((lane ^ o) << 2, __float_as_int(v))); }
;     ...
;                 for (int i = 0; i < 16; ++i) { const float o = ot[db][i] * inv - lam * xch[((sub * 4 + db) * 16 + i) * 64 + lane]; ot[db][i] = o; ss += o * o; }
;             ss += shx(ss, 32, lane);
	v_pk_mul_f32 v[134:135], v[54:55], v[54:55]
	v_pk_fma_f32 v[56:57], v[60:61], v[68:69], v[2:3] op_sel_hi:[1,0,1] neg_lo:[0,0,1] neg_hi:[0,0,1]
	v_pk_mul_f32 v[2:3], v[148:149], v[126:127]
	v_pk_mul_f32 v[60:61], v[56:57], v[56:57]
	v_pk_fma_f32 v[48:49], v[34:35], v[68:69], v[2:3] op_sel_hi:[1,0,1] neg_lo:[0,0,1] neg_hi:[0,0,1]
	v_pk_mul_f32 v[2:3], v[148:149], v[120:121]
	v_pk_mul_f32 v[62:63], v[50:51], v[50:51]
	v_pk_fma_f32 v[52:53], v[32:33], v[68:69], v[2:3] op_sel_hi:[1,0,1] neg_lo:[0,0,1] neg_hi:[0,0,1]
	v_pk_mul_f32 v[2:3], v[148:149], v[122:123]
	v_pk_mul_f32 v[120:121], v[52:53], v[52:53]
	v_pk_fma_f32 v[34:35], v[38:39], v[68:69], v[2:3] op_sel_hi:[1,0,1] neg_lo:[0,0,1] neg_hi:[0,0,1]
	v_pk_mul_f32 v[2:3], v[148:149], v[112:113]
	v_pk_mul_f32 v[124:125], v[48:49], v[48:49]
	v_pk_fma_f32 v[38:39], v[36:37], v[68:69], v[2:3] op_sel_hi:[1,0,1] neg_lo:[0,0,1] neg_hi:[0,0,1]
	v_pk_mul_f32 v[2:3], v[148:149], v[114:115]
	v_pk_mul_f32 v[112:113], v[38:39], v[38:39]
	v_pk_fma_f32 v[14:15], v[42:43], v[68:69], v[2:3] op_sel_hi:[1,0,1] neg_lo:[0,0,1] neg_hi:[0,0,1]
	v_pk_mul_f32 v[2:3], v[148:149], v[104:105]
	v_pk_mul_f32 v[122:123], v[34:35], v[34:35]
	v_pk_fma_f32 v[36:37], v[40:41], v[68:69], v[2:3] op_sel_hi:[1,0,1] neg_lo:[0,0,1] neg_hi:[0,0,1]
	v_pk_mul_f32 v[2:3], v[148:149], v[110:111]
	v_pk_mul_f32 v[40:41], v[36:37], v[36:37]
	v_pk_fma_f32 v[10:11], v[46:47], v[68:69], v[2:3] op_sel_hi:[1,0,1] neg_lo:[0,0,1] neg_hi:[0,0,1]
	v_pk_mul_f32 v[2:3], v[148:149], v[94:95]
	v_pk_mul_f32 v[42:43], v[14:15], v[14:15]
	v_pk_fma_f32 v[32:33], v[44:45], v[68:69], v[2:3] op_sel_hi:[1,0,1] neg_lo:[0,0,1] neg_hi:[0,0,1]
	v_pk_mul_f32 v[2:3], v[148:149], v[92:93]
	v_pk_mul_f32 v[44:45], v[32:33], v[32:33]
	v_pk_fma_f32 v[6:7], v[18:19], v[68:69], v[2:3] op_sel_hi:[1,0,1] neg_lo:[0,0,1] neg_hi:[0,0,1]
	v_pk_mul_f32 v[2:3], v[148:149], v[90:91]
	v_pk_mul_f32 v[46:47], v[10:11], v[10:11]
	v_pk_fma_f32 v[12:13], v[16:17], v[68:69], v[2:3] op_sel_hi:[1,0,1] neg_lo:[0,0,1] neg_hi:[0,0,1]
	v_pk_mul_f32 v[2:3], v[148:149], v[84:85]
	v_pk_mul_f32 v[16:17], v[12:13], v[12:13]
	v_pk_fma_f32 v[4:5], v[22:23], v[68:69], v[2:3] op_sel_hi:[1,0,1] neg_lo:[0,0,1] neg_hi:[0,0,1]
	v_pk_mul_f32 v[2:3], v[148:149], v[80:81]
	v_pk_mul_f32 v[18:19], v[6:7], v[6:7]
	v_pk_fma_f32 v[8:9], v[20:21], v[68:69], v[2:3] op_sel_hi:[1,0,1] neg_lo:[0,0,1] neg_hi:[0,0,1]
	v_pk_mul_f32 v[2:3], v[148:149], v[74:75]
	v_pk_mul_f32 v[20:21], v[8:9], v[8:9]
	v_pk_fma_f32 v[2:3], v[24:25], v[68:69], v[2:3] op_sel_hi:[1,0,1] neg_lo:[0,0,1] neg_hi:[0,0,1]
	v_add_f32_e32 v68, v144, v145
	v_add_f32_e32 v68, v68, v142
	v_add_f32_e32 v68, v68, v143
	v_add_f32_e32 v68, v68, v188
	v_add_f32_e32 v68, v68, v189
	v_add_f32_e32 v68, v68, v146
	v_add_f32_e32 v68, v68, v147
	v_add_f32_e32 v68, v68, v190
	v_add_f32_e32 v68, v68, v191
	v_add_f32_e32 v68, v68, v138
	v_add_f32_e32 v68, v68, v139
	v_add_f32_e32 v68, v68, v192
	v_add_f32_e32 v68, v68, v193
	v_add_f32_e32 v68, v68, v140
	v_add_f32_e32 v68, v68, v141
	v_add_f32_e32 v68, v68, v196
	v_add_f32_e32 v68, v68, v197
	v_add_f32_e32 v68, v68, v194
	v_add_f32_e32 v68, v68, v195
	v_add_f32_e32 v68, v68, v200
	v_add_f32_e32 v68, v68, v201
	v_add_f32_e32 v68, v68, v136
	v_add_f32_e32 v68, v68, v137
	v_add_f32_e32 v68, v68, v130
	v_add_f32_e32 v68, v68, v131
	v_add_f32_e32 v68, v68, v134
	v_add_f32_e32 v68, v68, v135
	v_add_f32_e32 v60, v68, v60
	v_add_f32_e32 v60, v60, v61
	v_add_f32_e32 v60, v60, v62
	v_add_f32_e32 v60, v60, v63
	v_add_f32_e32 v60, v60, v120
	v_add_f32_e32 v60, v60, v121
	v_add_f32_e32 v60, v60, v124
	v_add_f32_e32 v60, v60, v125
	v_add_f32_e32 v60, v60, v112
	v_add_f32_e32 v60, v60, v113
	v_add_f32_e32 v60, v60, v122
	v_add_f32_e32 v60, v60, v123
	v_add_f32_e32 v40, v60, v40
	v_add_f32_e32 v40, v40, v41
	v_add_f32_e32 v40, v40, v42
	v_add_f32_e32 v40, v40, v43
	v_add_f32_e32 v40, v40, v44
	v_add_f32_e32 v40, v40, v45
	v_add_f32_e32 v40, v40, v46
	v_add_f32_e32 v40, v40, v47
	v_add_f32_e32 v16, v40, v16
	v_add_f32_e32 v16, v16, v17
	v_add_f32_e32 v16, v16, v18
	v_add_f32_e32 v16, v16, v19
	v_add_f32_e32 v16, v16, v20
	v_pk_mul_f32 v[22:23], v[4:5], v[4:5]
	v_add_f32_e32 v16, v16, v21
	v_add_f32_e32 v16, v16, v22
	v_pk_mul_f32 v[24:25], v[2:3], v[2:3]
	v_add_f32_e32 v16, v16, v23
	v_add_f32_e32 v16, v16, v24
	v_add_f32_e32 v16, v16, v25
	v_add_f32_e32 v16, v16, v70
	v_add_f32_e32 v16, v16, v71
	v_add_f32_e32 v16, v16, v82
	v_pk_mul_f32 v[128:129], v[30:31], v[30:31]
	v_add_f32_e32 v16, v16, v83
	v_add_f32_e32 v16, v16, v128
	v_add_f32_e32 v16, v16, v129
	ds_bpermute_b32 v17, v99, v16
	s_waitcnt lgkmcnt(0)
; DI unsigned pk2(float a, float b) { f32x2 v = {a, b}; bf16x2_t r = __builtin_convertvector(v, bf16x2_t); return __builtin_bit_cast(unsigned, r); }
;     ...
;             const float rstd = osc / sqrtf(ss * (1.f / 128.f) + EPS);
;             bf16_t* orow = obase + (rowbase + q0 + r) * ldo + hd * 128;
; #pragma unroll
;             for (int db = 0; db < NDB; ++db)
; #pragma unroll
;                 for (int g = 0; g < 4; ++g) { const int d = 32 * db + 8 * g + 4 * h; const f32x4 gg = *(const f32x4*)(gsub + d);
;                     u32x2 o; o.x = pk2(ot[db][4 * g] * rstd * gg.x, ot[db][4 * g + 1] * rstd * gg.y); o.y = pk2(ot[db][4 * g + 2] * rstd * gg.z, ot[db][4 * g + 3] * rstd * gg.w);
;                     *(u32x2*)(orow + d) = o; }
	v_add_f32_e32 v16, v16, v17
	v_mov_b32_e32 v17, 0x358637bd
	v_fmamk_f32 v16, v16, 0x3c000000, v17
	v_cmp_gt_f32_e32 vcc, s30, v16
	v_mul_f32_e32 v17, 0x4f800000, v16
	s_nop 0
	v_cndmask_b32_e32 v16, v16, v17, vcc
	v_sqrt_f32_e32 v17, v16
	s_nop 0
	v_add_u32_e32 v18, -1, v17
	v_fma_f32 v19, -v18, v17, v16
	v_cmp_ge_f32_e64 s[0:1], 0, v19
	v_add_u32_e32 v19, 1, v17
	s_nop 0
	v_cndmask_b32_e64 v18, v17, v18, s[0:1]
	v_fma_f32 v17, -v19, v17, v16
	v_cmp_lt_f32_e64 s[0:1], 0, v17
	s_nop 1
	v_cndmask_b32_e64 v17, v18, v19, s[0:1]
	v_mul_f32_e32 v18, 0x37800000, v17
	v_cndmask_b32_e32 v17, v17, v18, vcc
	v_mov_b32_e32 v18, 0x260
	v_cmp_class_f32_e32 vcc, v16, v18
	s_nop 1
	v_cndmask_b32_e32 v16, v17, v16, vcc
	global_load_dwordx4 v[120:123], v[170:171], off offset:32
	global_load_dwordx4 v[124:127], v[170:171], off offset:64
	global_load_dwordx4 v[128:131], v[170:171], off offset:96
	global_load_dwordx4 v[132:135], v[170:171], off offset:128
	global_load_dwordx4 v[136:139], v[170:171], off offset:160
	global_load_dwordx4 v[140:143], v[170:171], off offset:192
	global_load_dwordx4 v[144:147], v[170:171], off offset:224
	global_load_dwordx4 v[224:227], v[170:171], off offset:256
	global_load_dwordx4 v[228:231], v[170:171], off offset:288
	global_load_dwordx4 v[236:239], v[170:171], off offset:320
	global_load_dwordx4 v[240:243], v[170:171], off offset:352
	global_load_dwordx4 v[200:203], v[170:171], off offset:384
	global_load_dwordx4 v[204:207], v[170:171], off offset:416
	global_load_dwordx4 v[40:43], v[170:171], off offset:448
	global_load_dwordx4 v[44:47], v[170:171], off offset:480
	v_div_scale_f32 v17, s[0:1], v16, v16, v210
	v_rcp_f32_e32 v18, v17
	s_nop 0
	v_fma_f32 v19, -v17, v18, 1.0
	v_fmac_f32_e32 v18, v19, v18
	v_div_scale_f32 v19, vcc, v210, v16, v210
	v_mul_f32_e32 v20, v19, v18
	v_fma_f32 v21, -v17, v20, v19
	v_fmac_f32_e32 v20, v21, v18
	v_fma_f32 v17, -v17, v20, v19
	v_div_fmas_f32 v17, v17, v18, v20
	v_div_fixup_f32 v16, v17, v16, v210
	v_pk_mul_f32 v[18:19], v[106:107], v[16:17] op_sel_hi:[1,0]
	v_pk_mul_f32 v[20:21], v[96:97], v[16:17] op_sel_hi:[1,0]
	s_waitcnt vmcnt(15)
	v_pk_mul_f32 v[18:19], v[26:27], v[18:19]
	v_pk_mul_f32 v[20:21], v[28:29], v[20:21]
	v_cvt_pk_bf16_f32 v18, v18, v19
	v_cvt_pk_bf16_f32 v19, v20, v21
	global_store_dwordx2 v[0:1], v[18:19], off
	v_pk_mul_f32 v[22:23], v[116:117], v[16:17] op_sel_hi:[1,0]
	v_pk_mul_f32 v[14:15], v[14:15], v[16:17] op_sel_hi:[1,0]
	v_pk_mul_f32 v[10:11], v[10:11], v[16:17] op_sel_hi:[1,0]
	v_pk_mul_f32 v[6:7], v[6:7], v[16:17] op_sel_hi:[1,0]
	v_pk_mul_f32 v[4:5], v[4:5], v[16:17] op_sel_hi:[1,0]
	v_pk_mul_f32 v[2:3], v[2:3], v[16:17] op_sel_hi:[1,0]
	s_waitcnt vmcnt(15)
	v_pk_mul_f32 v[18:19], v[120:121], v[22:23]
	v_pk_mul_f32 v[22:23], v[108:109], v[16:17] op_sel_hi:[1,0]
	v_cvt_pk_bf16_f32 v18, v18, v19
	v_pk_mul_f32 v[20:21], v[122:123], v[22:23]
	v_pk_mul_f32 v[22:23], v[118:119], v[16:17] op_sel_hi:[1,0]
	v_cvt_pk_bf16_f32 v19, v20, v21
	global_store_dwordx2 v[0:1], v[18:19], off offset:16
	s_waitcnt vmcnt(15)
	v_pk_mul_f32 v[18:19], v[124:125], v[22:23]
	v_pk_mul_f32 v[22:23], v[100:101], v[16:17] op_sel_hi:[1,0]
	v_cvt_pk_bf16_f32 v18, v18, v19
	v_pk_mul_f32 v[20:21], v[126:127], v[22:23]
	v_pk_mul_f32 v[22:23], v[102:103], v[16:17] op_sel_hi:[1,0]
	v_cvt_pk_bf16_f32 v19, v20, v21
	global_store_dwordx2 v[0:1], v[18:19], off offset:32
	s_waitcnt vmcnt(15)
	v_pk_mul_f32 v[18:19], v[128:129], v[22:23]
	v_pk_mul_f32 v[22:23], v[86:87], v[16:17] op_sel_hi:[1,0]
	v_cvt_pk_bf16_f32 v18, v18, v19
	v_pk_mul_f32 v[20:21], v[130:131], v[22:23]
	v_pk_mul_f32 v[22:23], v[88:89], v[16:17] op_sel_hi:[1,0]
	v_cvt_pk_bf16_f32 v19, v20, v21
	global_store_dwordx2 v[0:1], v[18:19], off offset:48
	s_waitcnt vmcnt(15)
; DI unsigned pk2(float a, float b) { f32x2 v = {a, b}; bf16x2_t r = __builtin_convertvector(v, bf16x2_t); return __builtin_bit_cast(unsigned, r); }
;     ...
;             for (int db = 0; db < NDB; ++db)
; #pragma unroll
;                 for (int g = 0; g < 4; ++g) { const int d = 32 * db + 8 * g + 4 * h; const f32x4 gg = *(const f32x4*)(gsub + d);
;                     u32x2 o; o.x = pk2(ot[db][4 * g] * rstd * gg.x, ot[db][4 * g + 1] * rstd * gg.y); o.y = pk2(ot[db][4 * g + 2] * rstd * gg.z, ot[db][4 * g + 3] * rstd * gg.w);
;                     *(u32x2*)(orow + d) = o; }
	v_pk_mul_f32 v[18:19], v[22:23], v[132:133]
	v_pk_mul_f32 v[22:23], v[76:77], v[16:17] op_sel_hi:[1,0]
	v_cvt_pk_bf16_f32 v18, v18, v19
	v_pk_mul_f32 v[20:21], v[22:23], v[134:135]
	v_pk_mul_f32 v[22:23], v[78:79], v[16:17] op_sel_hi:[1,0]
	v_cvt_pk_bf16_f32 v19, v20, v21
	global_store_dwordx2 v[0:1], v[18:19], off offset:64
	s_waitcnt vmcnt(15)
	v_pk_mul_f32 v[18:19], v[22:23], v[136:137]
	v_pk_mul_f32 v[22:23], v[72:73], v[16:17] op_sel_hi:[1,0]
	v_cvt_pk_bf16_f32 v18, v18, v19
	v_pk_mul_f32 v[20:21], v[22:23], v[138:139]
	v_pk_mul_f32 v[22:23], v[58:59], v[16:17] op_sel_hi:[1,0]
	v_cvt_pk_bf16_f32 v19, v20, v21
	global_store_dwordx2 v[0:1], v[18:19], off offset:80
	s_waitcnt vmcnt(15)
	v_pk_mul_f32 v[18:19], v[22:23], v[140:141]
	v_pk_mul_f32 v[22:23], v[54:55], v[16:17] op_sel_hi:[1,0]
	v_cvt_pk_bf16_f32 v18, v18, v19
	v_pk_mul_f32 v[20:21], v[22:23], v[142:143]
	v_pk_mul_f32 v[22:23], v[56:57], v[16:17] op_sel_hi:[1,0]
	v_cvt_pk_bf16_f32 v19, v20, v21
	global_store_dwordx2 v[0:1], v[18:19], off offset:96
	s_waitcnt vmcnt(15)
	v_pk_mul_f32 v[18:19], v[22:23], v[144:145]
	v_pk_mul_f32 v[22:23], v[50:51], v[16:17] op_sel_hi:[1,0]
	v_cvt_pk_bf16_f32 v18, v18, v19
	v_pk_mul_f32 v[20:21], v[22:23], v[146:147]
	v_pk_mul_f32 v[22:23], v[52:53], v[16:17] op_sel_hi:[1,0]
	v_cvt_pk_bf16_f32 v19, v20, v21
	global_store_dwordx2 v[0:1], v[18:19], off offset:112
	s_waitcnt vmcnt(15)
	v_pk_mul_f32 v[18:19], v[22:23], v[224:225]
	v_pk_mul_f32 v[22:23], v[48:49], v[16:17] op_sel_hi:[1,0]
	v_cvt_pk_bf16_f32 v18, v18, v19
	v_pk_mul_f32 v[20:21], v[22:23], v[226:227]
	v_pk_mul_f32 v[22:23], v[38:39], v[16:17] op_sel_hi:[1,0]
	v_cvt_pk_bf16_f32 v19, v20, v21
	global_store_dwordx2 v[0:1], v[18:19], off offset:128
	s_waitcnt vmcnt(15)
	v_pk_mul_f32 v[18:19], v[22:23], v[228:229]
	v_pk_mul_f32 v[22:23], v[34:35], v[16:17] op_sel_hi:[1,0]
	v_cvt_pk_bf16_f32 v18, v18, v19
	v_pk_mul_f32 v[20:21], v[22:23], v[230:231]
	v_pk_mul_f32 v[22:23], v[36:37], v[16:17] op_sel_hi:[1,0]
	v_cvt_pk_bf16_f32 v19, v20, v21
	global_store_dwordx2 v[0:1], v[18:19], off offset:144
	s_waitcnt vmcnt(15)
	v_pk_mul_f32 v[18:19], v[22:23], v[236:237]
	v_pk_mul_f32 v[14:15], v[14:15], v[238:239]
	v_cvt_pk_bf16_f32 v18, v18, v19
	v_cvt_pk_bf16_f32 v19, v14, v15
	global_store_dwordx2 v[0:1], v[18:19], off offset:160
	v_pk_mul_f32 v[14:15], v[32:33], v[16:17] op_sel_hi:[1,0]
	s_waitcnt vmcnt(15)
	v_pk_mul_f32 v[10:11], v[10:11], v[242:243]
	v_pk_mul_f32 v[14:15], v[14:15], v[240:241]
	s_nop 0
	v_cvt_pk_bf16_f32 v14, v14, v15
	v_cvt_pk_bf16_f32 v15, v10, v11
	global_store_dwordx2 v[0:1], v[14:15], off offset:176
	v_pk_mul_f32 v[10:11], v[12:13], v[16:17] op_sel_hi:[1,0]
	s_waitcnt vmcnt(15)
	v_pk_mul_f32 v[6:7], v[6:7], v[202:203]
	v_pk_mul_f32 v[10:11], v[10:11], v[200:201]
	s_nop 0
	v_cvt_pk_bf16_f32 v10, v10, v11
	v_cvt_pk_bf16_f32 v11, v6, v7
	global_store_dwordx2 v[0:1], v[10:11], off offset:192
	v_pk_mul_f32 v[6:7], v[8:9], v[16:17] op_sel_hi:[1,0]
	s_waitcnt vmcnt(15)
	v_pk_mul_f32 v[4:5], v[4:5], v[206:207]
	v_pk_mul_f32 v[6:7], v[6:7], v[204:205]
	s_nop 0
	v_cvt_pk_bf16_f32 v6, v6, v7
	v_cvt_pk_bf16_f32 v7, v4, v5
	global_store_dwordx2 v[0:1], v[6:7], off offset:208
	s_waitcnt vmcnt(15)
	v_pk_mul_f32 v[2:3], v[2:3], v[40:41]
	v_pk_mul_f32 v[4:5], v[64:65], v[16:17] op_sel_hi:[1,0]
	v_cvt_pk_bf16_f32 v2, v2, v3
	v_pk_mul_f32 v[4:5], v[4:5], v[42:43]
	v_pk_mul_f32 v[6:7], v[66:67], v[16:17] op_sel_hi:[1,0]
	v_cvt_pk_bf16_f32 v3, v4, v5
	global_store_dwordx2 v[0:1], v[2:3], off offset:224
	s_waitcnt vmcnt(15)
	v_pk_mul_f32 v[2:3], v[6:7], v[44:45]
	v_pk_mul_f32 v[6:7], v[30:31], v[16:17] op_sel_hi:[1,0]
	v_cvt_pk_bf16_f32 v2, v2, v3
	v_pk_mul_f32 v[4:5], v[6:7], v[46:47]
	s_nop 0
	v_cvt_pk_bf16_f32 v3, v4, v5
	global_store_dwordx2 v[0:1], v[2:3], off offset:240
	s_branch .LBB0_495
